# no grid barrier between Hyena order-0 and order-1 phases: order 1 reads only the z1T channels its own workgroup wrote (workgroup barrier at loop top suffices)
# speedup vs baseline: 1.0253x; 1.0039x over previous
; #define LAS __attribute__((address_space(3)))
; __device__ __forceinline__ unsigned xb_add(unsigned* p, unsigned v) { return __hip_atomic_fetch_add(p, v, __ATOMIC_RELAXED, __HIP_MEMORY_SCOPE_AGENT); }
; __device__ __forceinline__ unsigned xb_xcc_id() { return (unsigned)__builtin_amdgcn_s_getreg((3 << 11) | 20) & 0xFu; }
; __device__ __forceinline__ void xcd_barrier() {
;     asm volatile("s_waitcnt vmcnt(0)" ::: "memory");
;     __syncthreads();
;     if (threadIdx.x == 0) {
;         unsigned* bar = (unsigned*)(((unsigned char*)ldp(38)) + OFF_BAR);
;         volatile LAS unsigned* st = (volatile LAS unsigned*)(LAS unsigned char*)(g_smem + LDS_BYTES - 1024);
;         const unsigned x = xb_xcc_id();
;         __builtin_amdgcn_s_waitcnt(0);
;         unsigned nloc = st[0], nx = st[1];
;         if (nloc == 0u) { xcd_barrier_complete(bar, x, nloc, nx); st[0] = nloc; st[1] = nx; }
;         const unsigned old = xb_add(&bar[XB_XSUB(x)], 1u);
; __global__ void __launch_bounds__(512, 2) fwd_megakernel(Params p) {
;     ...
;         if (sync) { if (it == 0) cg::this_grid().sync(); else xcd_barrier(); if ((REP >> 12) & 1) xcd_barrier(); }
.LBB0_767:
	v_readlane_b32 s0, v255, 54
	v_readlane_b32 s1, v255, 55
	s_andn2_b64 vcc, exec, s[0:1]
	s_mov_b32 s70, 0x7f800000
	s_cbranch_vccnz .LBB0_837
	s_mul_i32 s0, s90, 0xcd
	s_bfe_u32 s0, s0, 0x4000c
	s_mul_i32 s0, s0, 0xffffffec
	s_add_i32 s0, s0, s90
	s_cmp_eq_u32 s0, 7
	s_cbranch_scc1 .LBB0_837
	s_cmp_lg_u32 s90, 0
	s_cbranch_scc0 .LBB0_781
	s_waitcnt vmcnt(0)
	s_waitcnt lgkmcnt(0)
	s_barrier
	s_mov_b64 s[0:1], exec
	v_readlane_b32 s6, v254, 0
	v_readlane_b32 s7, v254, 1
	s_and_b64 s[6:7], s[0:1], s[6:7]
	s_mov_b64 exec, s[6:7]
	s_cbranch_execz .LBB0_824
	s_cmp_lg_u32 s40, -1
	s_cselect_b32 s5, s40, 0
	s_cselect_b32 s6, s41, 0
	s_waitcnt vmcnt(3)
	v_mov_b32_e32 v0, s5
	v_mov_b32_e32 v1, s6
	s_waitcnt vmcnt(2)
	flat_load_dwordx2 v[4:5], v[0:1] sc0 sc1
	s_waitcnt vmcnt(0)
	s_add_i32 s14, 0, 0x23c00
	v_mov_b32_e32 v0, s14
	s_getreg_b32 s5, hwreg(HW_REG_XCC_ID, 0, 4)
	s_waitcnt vmcnt(0) expcnt(0) lgkmcnt(0)
	ds_read_b32 v2, v0
	s_add_i32 s15, 0, 0x23c04
	v_mov_b32_e32 v0, s15
	ds_read_b32 v0, v0
	s_and_b32 s5, s5, 15
	s_waitcnt lgkmcnt(1)
	v_cmp_ne_u32_e32 vcc, 0, v2
	v_readfirstlane_b32 s7, v5
	v_readfirstlane_b32 s6, v4
	s_cbranch_vccnz .LBB0_787
	v_readlane_b32 s8, v254, 19
	v_readlane_b32 s9, v254, 20
	s_load_dwordx2 s[12:13], s[8:9], 0x0
	s_load_dword s11, s[8:9], 0x8
	s_add_u32 s8, s6, 0x22ca0200
	s_addc_u32 s9, s7, 0
	s_add_u32 s10, s6, 0x22ca0400
	s_waitcnt lgkmcnt(0)
	s_mul_i32 s24, s13, s12
	s_mul_i32 s24, s24, s11
	s_addc_u32 s11, s7, 0
	s_add_u32 s12, s6, 0x22ca0500
	s_addc_u32 s13, s7, 0
	s_add_u32 s16, s6, 0x22ca0600
	s_addc_u32 s17, s7, 0
	s_add_u32 s18, s6, 0x22ca0700
	s_addc_u32 s19, s7, 0
	s_add_u32 s20, s6, 0x22ca0800
	s_addc_u32 s21, s7, 0
	s_add_u32 s22, s6, 0x22ca0900
	s_addc_u32 s23, s7, 0
	s_add_u32 s28, s6, 0x22ca0a00
	s_addc_u32 s29, s7, 0
	s_add_u32 s42, s6, 0x22ca0b00
	s_addc_u32 s43, s7, 0
	s_add_u32 s44, s6, 0x22ca0c00
	s_addc_u32 s45, s7, 0
	s_add_u32 s46, s6, 0x22ca0d00
	s_addc_u32 s47, s7, 0
	s_add_u32 s48, s6, 0x22ca0e00
	s_addc_u32 s49, s7, 0
	s_add_u32 s50, s6, 0x22ca0f00
	s_addc_u32 s51, s7, 0
	s_add_u32 s52, s6, 0x22ca1000
	s_addc_u32 s53, s7, 0
	s_add_u32 s56, s6, 0x22ca1100
	s_addc_u32 s57, s7, 0
	s_add_u32 s58, s6, 0x22ca1200
	s_addc_u32 s59, s7, 0
	s_add_u32 s60, s6, 0x22ca1300
	s_addc_u32 s61, s7, 0
	s_mov_b32 s27, 1
	s_branch .LBB0_774
